# baseline (speedup 1.0000x reference)
;     __device__ bool next(int i, Unit& u) const { const int L = i * G + c; if (L >= nwg) return false; u.pm = L % nM; u.pn = L / nM; u.ord = i; return true; }
; template <class Epi, class Sched, bool ALIGN_EPI = false, bool SP2 = false>
; __device__ __forceinline__ void gemm_phase(PG8_LAS unsigned char* lds, const Gemm g, const Sched& S, const Epi& E) {
;     ...
;         const bool has_next = S.next(ui + 1, nxt);
;         const char* nA = has_next ? (const char*)g.A + (size_t)nxt.pm * tstep : cA; const char* nB = has_next ? (const char*)g.Bt + (size_t)nxt.pn * tstep : cB;
;         for (int t = 0; t < nt; t += 2) {
;             const bool last = (t == nt - 2);
;             const char* a1 = cA + (size_t)(t + 1) * kstep;
;             const char* a2 = last ? nA : cA + (size_t)(t + 2) * kstep; const char* b2 = last ? nB : cB + (size_t)(t + 2) * kstep;
;             const char* a3 = a2 + kstep; const char* b3 = b2 + kstep;
;     ...
; #pragma unroll
;         for (int a = 0; a < 2; ++a)
; #pragma unroll
;             for (int b = 0; b < 2; ++b)
; #pragma unroll
;                 for (int m = 0; m < 4; ++m)
; #pragma unroll
;                     for (int n = 0; n < 2; ++n) acc[a][b][m][n] = (f32x4){0.f, 0.f, 0.f, 0.f};
.LBB0_167:
	s_ashr_i32 s31, s30, 31
	s_lshl_b64 s[34:35], s[30:31], 19
	s_add_u32 s34, s81, s34
	s_addc_u32 s35, s89, s35
	s_and_b64 s[36:37], s[6:7], exec
	s_cselect_b32 s31, s35, s65
	s_cselect_b32 s42, s34, s64
	s_ashr_i32 s29, s28, 31
	s_lshl_b64 s[36:37], s[28:29], 19
	s_add_u32 s36, s90, s36
	s_addc_u32 s37, s96, s37
	s_and_b64 s[44:45], s[6:7], exec
	s_cselect_b32 s29, s37, s39
	s_cselect_b32 s43, s36, s38
	s_add_u32 s44, s38, 0x100
	s_addc_u32 s45, s39, 0
	s_add_u32 s64, s64, 0x40080
	v_mov_b32_e32 v0, 0
	s_addc_u32 s65, s65, 0
	s_mov_b32 s46, -2
	v_mov_b32_e32 v1, v0
	v_mov_b32_e32 v2, v0
	v_mov_b32_e32 v3, v0
	v_mov_b32_e32 v8, v0
	v_mov_b32_e32 v9, v0
	v_mov_b32_e32 v10, v0
	v_mov_b32_e32 v11, v0
	v_mov_b32_e32 v16, v0
	v_mov_b32_e32 v17, v0
	v_mov_b32_e32 v18, v0
	v_mov_b32_e32 v19, v0
	v_mov_b32_e32 v24, v0
	v_mov_b32_e32 v25, v0
	v_mov_b32_e32 v26, v0
	v_mov_b32_e32 v27, v0
	v_mov_b32_e32 v32, v0
	v_mov_b32_e32 v33, v0
	v_mov_b32_e32 v34, v0
	v_mov_b32_e32 v35, v0
	v_mov_b32_e32 v40, v0
	v_mov_b32_e32 v41, v0
	v_mov_b32_e32 v42, v0
	v_mov_b32_e32 v43, v0
	v_mov_b32_e32 v48, v0
	v_mov_b32_e32 v49, v0
	v_mov_b32_e32 v50, v0
	v_mov_b32_e32 v51, v0
	v_mov_b32_e32 v56, v0
	v_mov_b32_e32 v57, v0
	v_mov_b32_e32 v58, v0
	v_mov_b32_e32 v59, v0
	v_mov_b32_e32 v4, v0
	v_mov_b32_e32 v5, v0
	v_mov_b32_e32 v6, v0
	v_mov_b32_e32 v7, v0
	v_mov_b32_e32 v12, v0
	v_mov_b32_e32 v13, v0
	v_mov_b32_e32 v14, v0
	v_mov_b32_e32 v15, v0
	v_mov_b32_e32 v20, v0
	v_mov_b32_e32 v21, v0
	v_mov_b32_e32 v22, v0
	v_mov_b32_e32 v23, v0
	v_mov_b32_e32 v28, v0
	v_mov_b32_e32 v29, v0
	v_mov_b32_e32 v30, v0
	v_mov_b32_e32 v31, v0
	v_mov_b32_e32 v36, v0
	v_mov_b32_e32 v37, v0
	v_mov_b32_e32 v38, v0
	v_mov_b32_e32 v39, v0
	v_mov_b32_e32 v44, v0
	v_mov_b32_e32 v45, v0
	v_mov_b32_e32 v46, v0
	v_mov_b32_e32 v47, v0
	v_mov_b32_e32 v52, v0
	v_mov_b32_e32 v53, v0
	v_mov_b32_e32 v54, v0
	v_mov_b32_e32 v55, v0
	v_mov_b32_e32 v60, v0
	v_mov_b32_e32 v61, v0
	v_mov_b32_e32 v62, v0
	v_mov_b32_e32 v63, v0
	v_mov_b32_e32 v64, v0
	v_mov_b32_e32 v65, v0
	v_mov_b32_e32 v66, v0
	v_mov_b32_e32 v67, v0
	v_mov_b32_e32 v72, v0
	v_mov_b32_e32 v73, v0
	v_mov_b32_e32 v74, v0
	v_mov_b32_e32 v75, v0
	v_mov_b32_e32 v80, v0
	v_mov_b32_e32 v81, v0
	v_mov_b32_e32 v82, v0
	v_mov_b32_e32 v83, v0
	v_mov_b32_e32 v88, v0
	v_mov_b32_e32 v89, v0
	v_mov_b32_e32 v90, v0
	v_mov_b32_e32 v91, v0
	v_mov_b32_e32 v96, v0
	v_mov_b32_e32 v97, v0
	v_mov_b32_e32 v98, v0
	v_mov_b32_e32 v99, v0
	v_mov_b32_e32 v104, v0
	v_mov_b32_e32 v105, v0
	v_mov_b32_e32 v106, v0
	v_mov_b32_e32 v107, v0
	v_mov_b32_e32 v112, v0
	v_mov_b32_e32 v113, v0
	v_mov_b32_e32 v114, v0
	v_mov_b32_e32 v115, v0
	v_mov_b32_e32 v120, v0
	v_mov_b32_e32 v121, v0
	v_mov_b32_e32 v122, v0
	v_mov_b32_e32 v123, v0
	v_mov_b32_e32 v68, v0
	v_mov_b32_e32 v69, v0
	v_mov_b32_e32 v70, v0
	v_mov_b32_e32 v71, v0
	v_mov_b32_e32 v76, v0
	v_mov_b32_e32 v77, v0
	v_mov_b32_e32 v78, v0
	v_mov_b32_e32 v79, v0
	v_mov_b32_e32 v84, v0
	v_mov_b32_e32 v85, v0
	v_mov_b32_e32 v86, v0
	v_mov_b32_e32 v87, v0
	v_mov_b32_e32 v92, v0
	v_mov_b32_e32 v93, v0
	v_mov_b32_e32 v94, v0
	v_mov_b32_e32 v95, v0
	v_mov_b32_e32 v100, v0
	v_mov_b32_e32 v101, v0
	v_mov_b32_e32 v102, v0
	v_mov_b32_e32 v103, v0
	v_mov_b32_e32 v108, v0
	v_mov_b32_e32 v109, v0
	v_mov_b32_e32 v110, v0
	v_mov_b32_e32 v111, v0
	v_mov_b32_e32 v116, v0
	v_mov_b32_e32 v117, v0
	v_mov_b32_e32 v118, v0
	v_mov_b32_e32 v119, v0
	v_mov_b32_e32 v124, v0
	v_mov_b32_e32 v125, v0
	v_mov_b32_e32 v126, v0
	v_mov_b32_e32 v127, v0
	.p2align 6

; __device__ __forceinline__ void attn_unit(LAS unsigned char* lds, bf16_t* Qm, const bf16_t* __restrict__ Kb, const bf16_t* __restrict__ Vt,
;                                           int b, int h, int qb, int lgS, float lam, float oscale, const float* __restrict__ subg, float* stash) {
;     ...
;         for (int t = 0; t < NT - 1; ++t) {
.Lmy_noprio:
	.p2align 6
